# zero64
# baseline (speedup 1.0000x reference)
.LBB0_250:
	s_ashr_i32 s47, s46, 31
	s_lshl_b64 s[48:49], s[46:47], 20
	v_readlane_b32 s26, v254, 61
	s_add_u32 s48, s26, s48
	v_readlane_b32 s26, v254, 62
	s_addc_u32 s49, s26, s49
	s_and_b64 s[50:51], s[38:39], exec
	s_cselect_b32 s26, s49, s63
	s_cselect_b32 s47, s48, s62
	s_ashr_i32 s45, s44, 31
	s_lshl_b64 s[50:51], s[44:45], 20
	s_add_u32 s50, s6, s50
	s_addc_u32 s51, s9, s51
	s_and_b64 s[64:65], s[38:39], exec
	s_cselect_b32 s45, s51, s61
	s_cselect_b32 s72, s50, s60
	s_add_u32 s73, s60, 0x100
	s_addc_u32 s76, s61, 0
	s_add_u32 s60, s62, 0x80080
	v_mov_b64_e32 v[2:3], 0
	v_mov_b64_e32 v[4:5], 0
	v_mov_b64_e32 v[6:7], 0
	v_mov_b64_e32 v[8:9], 0
	v_mov_b64_e32 v[10:11], 0
	v_mov_b64_e32 v[12:13], 0
	v_mov_b64_e32 v[14:15], 0
	v_mov_b64_e32 v[16:17], 0
	v_mov_b64_e32 v[18:19], 0
	v_mov_b64_e32 v[20:21], 0
	v_mov_b64_e32 v[22:23], 0
	v_mov_b64_e32 v[24:25], 0
	v_mov_b64_e32 v[26:27], 0
	v_mov_b64_e32 v[28:29], 0
	v_mov_b64_e32 v[30:31], 0
	v_mov_b64_e32 v[32:33], 0
	v_mov_b64_e32 v[34:35], 0
	v_mov_b64_e32 v[36:37], 0
	v_mov_b64_e32 v[38:39], 0
	v_mov_b64_e32 v[40:41], 0
	v_mov_b64_e32 v[42:43], 0
	v_mov_b64_e32 v[44:45], 0
	v_mov_b64_e32 v[46:47], 0
	v_mov_b64_e32 v[48:49], 0
	v_mov_b64_e32 v[50:51], 0
	v_mov_b64_e32 v[52:53], 0
	v_mov_b64_e32 v[54:55], 0
	v_mov_b64_e32 v[56:57], 0
	v_mov_b64_e32 v[58:59], 0
	v_mov_b64_e32 v[60:61], 0
	v_mov_b64_e32 v[62:63], 0
	v_mov_b64_e32 v[64:65], 0
	v_mov_b64_e32 v[66:67], 0
	v_mov_b64_e32 v[68:69], 0
	v_mov_b64_e32 v[70:71], 0
	v_mov_b64_e32 v[72:73], 0
	v_mov_b64_e32 v[74:75], 0
	v_mov_b64_e32 v[76:77], 0
	v_mov_b64_e32 v[78:79], 0
	v_mov_b64_e32 v[80:81], 0
	v_mov_b64_e32 v[82:83], 0
	v_mov_b64_e32 v[84:85], 0
	v_mov_b64_e32 v[86:87], 0
	v_mov_b64_e32 v[88:89], 0
	v_mov_b64_e32 v[90:91], 0
	v_mov_b64_e32 v[92:93], 0
	v_mov_b64_e32 v[94:95], 0
	v_mov_b64_e32 v[96:97], 0
	v_mov_b64_e32 v[98:99], 0
	v_mov_b64_e32 v[100:101], 0
	v_mov_b64_e32 v[102:103], 0
	v_mov_b64_e32 v[104:105], 0
	v_mov_b64_e32 v[106:107], 0
	v_mov_b64_e32 v[108:109], 0
	v_mov_b64_e32 v[110:111], 0
	v_mov_b64_e32 v[112:113], 0
	v_mov_b64_e32 v[114:115], 0
	v_mov_b64_e32 v[116:117], 0
	v_mov_b64_e32 v[118:119], 0
	v_mov_b64_e32 v[120:121], 0
	v_mov_b64_e32 v[122:123], 0
	v_mov_b64_e32 v[124:125], 0
	v_mov_b64_e32 v[126:127], 0
	v_mov_b64_e32 v[128:129], 0
	s_addc_u32 s61, s63, 0
	s_mov_b32 s77, -2

.LBB0_324:
	s_ashr_i32 s43, s42, 31
	s_lshl_b64 s[48:49], s[42:43], 18
	s_add_u32 s48, s9, s48
	s_addc_u32 s49, s14, s49
	s_and_b64 s[50:51], s[38:39], exec
	s_cselect_b32 s43, s49, s61
	s_cselect_b32 s47, s48, s60
	s_ashr_i32 s45, s44, 31
	s_lshl_b64 s[50:51], s[44:45], 18
	s_add_u32 s50, s17, s50
	s_addc_u32 s51, s22, s51
	s_and_b64 s[62:63], s[38:39], exec
	s_cselect_b32 s45, s51, s53
	s_cselect_b32 s72, s50, s52
	s_add_u32 s73, s52, 0x100
	s_addc_u32 s76, s53, 0
	s_add_u32 s52, s60, 0x20080
	v_mov_b64_e32 v[2:3], 0
	v_mov_b64_e32 v[4:5], 0
	v_mov_b64_e32 v[6:7], 0
	v_mov_b64_e32 v[8:9], 0
	v_mov_b64_e32 v[10:11], 0
	v_mov_b64_e32 v[12:13], 0
	v_mov_b64_e32 v[14:15], 0
	v_mov_b64_e32 v[16:17], 0
	v_mov_b64_e32 v[18:19], 0
	v_mov_b64_e32 v[20:21], 0
	v_mov_b64_e32 v[22:23], 0
	v_mov_b64_e32 v[24:25], 0
	v_mov_b64_e32 v[26:27], 0
	v_mov_b64_e32 v[28:29], 0
	v_mov_b64_e32 v[30:31], 0
	v_mov_b64_e32 v[32:33], 0
	v_mov_b64_e32 v[34:35], 0
	v_mov_b64_e32 v[36:37], 0
	v_mov_b64_e32 v[38:39], 0
	v_mov_b64_e32 v[40:41], 0
	v_mov_b64_e32 v[42:43], 0
	v_mov_b64_e32 v[44:45], 0
	v_mov_b64_e32 v[46:47], 0
	v_mov_b64_e32 v[48:49], 0
	v_mov_b64_e32 v[50:51], 0
	v_mov_b64_e32 v[52:53], 0
	v_mov_b64_e32 v[54:55], 0
	v_mov_b64_e32 v[56:57], 0
	v_mov_b64_e32 v[58:59], 0
	v_mov_b64_e32 v[60:61], 0
	v_mov_b64_e32 v[62:63], 0
	v_mov_b64_e32 v[64:65], 0
	v_mov_b64_e32 v[66:67], 0
	v_mov_b64_e32 v[68:69], 0
	v_mov_b64_e32 v[70:71], 0
	v_mov_b64_e32 v[72:73], 0
	v_mov_b64_e32 v[74:75], 0
	v_mov_b64_e32 v[76:77], 0
	v_mov_b64_e32 v[78:79], 0
	v_mov_b64_e32 v[80:81], 0
	v_mov_b64_e32 v[82:83], 0
	v_mov_b64_e32 v[84:85], 0
	v_mov_b64_e32 v[86:87], 0
	v_mov_b64_e32 v[88:89], 0
	v_mov_b64_e32 v[90:91], 0
	v_mov_b64_e32 v[92:93], 0
	v_mov_b64_e32 v[94:95], 0
	v_mov_b64_e32 v[96:97], 0
	v_mov_b64_e32 v[98:99], 0
	v_mov_b64_e32 v[100:101], 0
	v_mov_b64_e32 v[102:103], 0
	v_mov_b64_e32 v[104:105], 0
	v_mov_b64_e32 v[106:107], 0
	v_mov_b64_e32 v[108:109], 0
	v_mov_b64_e32 v[110:111], 0
	v_mov_b64_e32 v[112:113], 0
	v_mov_b64_e32 v[114:115], 0
	v_mov_b64_e32 v[116:117], 0
	v_mov_b64_e32 v[118:119], 0
	v_mov_b64_e32 v[120:121], 0
	v_mov_b64_e32 v[122:123], 0
	v_mov_b64_e32 v[124:125], 0
	v_mov_b64_e32 v[126:127], 0
	v_mov_b64_e32 v[128:129], 0
	s_addc_u32 s53, s61, 0
	s_mov_b32 s77, -2

.LBB0_386:
	s_ashr_i32 s47, s46, 31
	s_lshl_b64 s[48:49], s[46:47], 20
	v_readlane_b32 s45, v254, 61
	s_add_u32 s48, s45, s48
	v_readlane_b32 s45, v254, 62
	s_addc_u32 s49, s45, s49
	s_and_b64 s[50:51], s[38:39], exec
	s_cselect_b32 s47, s49, s61
	s_cselect_b32 s70, s48, s60
	s_ashr_i32 s45, s44, 31
	s_lshl_b64 s[50:51], s[44:45], 20
	s_add_u32 s50, s9, s50
	s_addc_u32 s51, s14, s51
	s_and_b64 s[62:63], s[38:39], exec
	s_cselect_b32 s45, s51, s53
	s_cselect_b32 s71, s50, s52
	s_add_u32 s72, s52, 0x100
	s_addc_u32 s73, s53, 0
	s_add_u32 s52, s60, 0x80080
	v_mov_b64_e32 v[2:3], 0
	v_mov_b64_e32 v[4:5], 0
	v_mov_b64_e32 v[6:7], 0
	v_mov_b64_e32 v[8:9], 0
	v_mov_b64_e32 v[10:11], 0
	v_mov_b64_e32 v[12:13], 0
	v_mov_b64_e32 v[14:15], 0
	v_mov_b64_e32 v[16:17], 0
	v_mov_b64_e32 v[18:19], 0
	v_mov_b64_e32 v[20:21], 0
	v_mov_b64_e32 v[22:23], 0
	v_mov_b64_e32 v[24:25], 0
	v_mov_b64_e32 v[26:27], 0
	v_mov_b64_e32 v[28:29], 0
	v_mov_b64_e32 v[30:31], 0
	v_mov_b64_e32 v[32:33], 0
	v_mov_b64_e32 v[34:35], 0
	v_mov_b64_e32 v[36:37], 0
	v_mov_b64_e32 v[38:39], 0
	v_mov_b64_e32 v[40:41], 0
	v_mov_b64_e32 v[42:43], 0
	v_mov_b64_e32 v[44:45], 0
	v_mov_b64_e32 v[46:47], 0
	v_mov_b64_e32 v[48:49], 0
	v_mov_b64_e32 v[50:51], 0
	v_mov_b64_e32 v[52:53], 0
	v_mov_b64_e32 v[54:55], 0
	v_mov_b64_e32 v[56:57], 0
	v_mov_b64_e32 v[58:59], 0
	v_mov_b64_e32 v[60:61], 0
	v_mov_b64_e32 v[62:63], 0
	v_mov_b64_e32 v[64:65], 0
	v_mov_b64_e32 v[66:67], 0
	v_mov_b64_e32 v[68:69], 0
	v_mov_b64_e32 v[70:71], 0
	v_mov_b64_e32 v[72:73], 0
	v_mov_b64_e32 v[74:75], 0
	v_mov_b64_e32 v[76:77], 0
	v_mov_b64_e32 v[78:79], 0
	v_mov_b64_e32 v[80:81], 0
	v_mov_b64_e32 v[82:83], 0
	v_mov_b64_e32 v[84:85], 0
	v_mov_b64_e32 v[86:87], 0
	v_mov_b64_e32 v[88:89], 0
	v_mov_b64_e32 v[90:91], 0
	v_mov_b64_e32 v[92:93], 0
	v_mov_b64_e32 v[94:95], 0
	v_mov_b64_e32 v[96:97], 0
	v_mov_b64_e32 v[98:99], 0
	v_mov_b64_e32 v[100:101], 0
	v_mov_b64_e32 v[102:103], 0
	v_mov_b64_e32 v[104:105], 0
	v_mov_b64_e32 v[106:107], 0
	v_mov_b64_e32 v[108:109], 0
	v_mov_b64_e32 v[110:111], 0
	v_mov_b64_e32 v[112:113], 0
	v_mov_b64_e32 v[114:115], 0
	v_mov_b64_e32 v[116:117], 0
	v_mov_b64_e32 v[118:119], 0
	v_mov_b64_e32 v[120:121], 0
	v_mov_b64_e32 v[122:123], 0
	v_mov_b64_e32 v[124:125], 0
	v_mov_b64_e32 v[126:127], 0
	v_mov_b64_e32 v[128:129], 0
	s_addc_u32 s53, s61, 0
	s_mov_b32 s76, -2

.LBB0_407:
	s_add_i32 s60, s64, -2
	s_add_u32 s61, s50, 0x100
	s_addc_u32 s80, s51, 0
	s_add_u32 s50, s52, 0x80
	v_mov_b64_e32 v[2:3], 0
	v_mov_b64_e32 v[4:5], 0
	v_mov_b64_e32 v[6:7], 0
	v_mov_b64_e32 v[8:9], 0
	v_mov_b64_e32 v[10:11], 0
	v_mov_b64_e32 v[12:13], 0
	v_mov_b64_e32 v[14:15], 0
	v_mov_b64_e32 v[16:17], 0
	v_mov_b64_e32 v[18:19], 0
	v_mov_b64_e32 v[20:21], 0
	v_mov_b64_e32 v[22:23], 0
	v_mov_b64_e32 v[24:25], 0
	v_mov_b64_e32 v[26:27], 0
	v_mov_b64_e32 v[28:29], 0
	v_mov_b64_e32 v[30:31], 0
	v_mov_b64_e32 v[32:33], 0
	v_mov_b64_e32 v[34:35], 0
	v_mov_b64_e32 v[36:37], 0
	v_mov_b64_e32 v[38:39], 0
	v_mov_b64_e32 v[40:41], 0
	v_mov_b64_e32 v[42:43], 0
	v_mov_b64_e32 v[44:45], 0
	v_mov_b64_e32 v[46:47], 0
	v_mov_b64_e32 v[48:49], 0
	v_mov_b64_e32 v[50:51], 0
	v_mov_b64_e32 v[52:53], 0
	v_mov_b64_e32 v[54:55], 0
	v_mov_b64_e32 v[56:57], 0
	v_mov_b64_e32 v[58:59], 0
	v_mov_b64_e32 v[60:61], 0
	v_mov_b64_e32 v[62:63], 0
	v_mov_b64_e32 v[64:65], 0
	v_mov_b64_e32 v[66:67], 0
	v_mov_b64_e32 v[68:69], 0
	v_mov_b64_e32 v[70:71], 0
	v_mov_b64_e32 v[72:73], 0
	v_mov_b64_e32 v[74:75], 0
	v_mov_b64_e32 v[76:77], 0
	v_mov_b64_e32 v[78:79], 0
	v_mov_b64_e32 v[80:81], 0
	v_mov_b64_e32 v[82:83], 0
	v_mov_b64_e32 v[84:85], 0
	v_mov_b64_e32 v[86:87], 0
	v_mov_b64_e32 v[88:89], 0
	v_mov_b64_e32 v[90:91], 0
	v_mov_b64_e32 v[92:93], 0
	v_mov_b64_e32 v[94:95], 0
	v_mov_b64_e32 v[96:97], 0
	v_mov_b64_e32 v[98:99], 0
	v_mov_b64_e32 v[100:101], 0
	v_mov_b64_e32 v[102:103], 0
	v_mov_b64_e32 v[104:105], 0
	v_mov_b64_e32 v[106:107], 0
	v_mov_b64_e32 v[108:109], 0
	v_mov_b64_e32 v[110:111], 0
	v_mov_b64_e32 v[112:113], 0
	v_mov_b64_e32 v[114:115], 0
	v_mov_b64_e32 v[116:117], 0
	v_mov_b64_e32 v[118:119], 0
	v_mov_b64_e32 v[120:121], 0
	v_mov_b64_e32 v[122:123], 0
	v_mov_b64_e32 v[124:125], 0
	v_mov_b64_e32 v[126:127], 0
	v_mov_b64_e32 v[128:129], 0
	s_addc_u32 s51, s53, 0
	s_mov_b32 s52, 0

.LBB0_431:
	s_ashr_i32 s43, s42, 31
	s_lshl_b64 s[44:45], s[42:43], 20
	v_readlane_b32 s6, v254, 61
	s_add_u32 s44, s6, s44
	v_readlane_b32 s6, v254, 62
	s_addc_u32 s45, s6, s45
	s_and_b64 s[46:47], s[38:39], exec
	s_cselect_b32 s6, s45, s53
	s_cselect_b32 s14, s44, s52
	s_ashr_i32 s41, s40, 31
	s_lshl_b64 s[46:47], s[40:41], 20
	s_add_u32 s46, s5, s46
	s_addc_u32 s47, s63, s47
	s_and_b64 s[60:61], s[38:39], exec
	s_cselect_b32 s17, s47, s51
	s_cselect_b32 s41, s46, s50
	s_add_u32 s43, s50, 0x100
	s_addc_u32 s49, s51, 0
	s_add_u32 s50, s52, 0x80080
	v_mov_b64_e32 v[2:3], 0
	v_mov_b64_e32 v[4:5], 0
	v_mov_b64_e32 v[6:7], 0
	v_mov_b64_e32 v[8:9], 0
	v_mov_b64_e32 v[10:11], 0
	v_mov_b64_e32 v[12:13], 0
	v_mov_b64_e32 v[14:15], 0
	v_mov_b64_e32 v[16:17], 0
	v_mov_b64_e32 v[18:19], 0
	v_mov_b64_e32 v[20:21], 0
	v_mov_b64_e32 v[22:23], 0
	v_mov_b64_e32 v[24:25], 0
	v_mov_b64_e32 v[26:27], 0
	v_mov_b64_e32 v[28:29], 0
	v_mov_b64_e32 v[30:31], 0
	v_mov_b64_e32 v[32:33], 0
	v_mov_b64_e32 v[34:35], 0
	v_mov_b64_e32 v[36:37], 0
	v_mov_b64_e32 v[38:39], 0
	v_mov_b64_e32 v[40:41], 0
	v_mov_b64_e32 v[42:43], 0
	v_mov_b64_e32 v[44:45], 0
	v_mov_b64_e32 v[46:47], 0
	v_mov_b64_e32 v[48:49], 0
	v_mov_b64_e32 v[50:51], 0
	v_mov_b64_e32 v[52:53], 0
	v_mov_b64_e32 v[54:55], 0
	v_mov_b64_e32 v[56:57], 0
	v_mov_b64_e32 v[58:59], 0
	v_mov_b64_e32 v[60:61], 0
	v_mov_b64_e32 v[62:63], 0
	v_mov_b64_e32 v[64:65], 0
	v_mov_b64_e32 v[66:67], 0
	v_mov_b64_e32 v[68:69], 0
	v_mov_b64_e32 v[70:71], 0
	v_mov_b64_e32 v[72:73], 0
	v_mov_b64_e32 v[74:75], 0
	v_mov_b64_e32 v[76:77], 0
	v_mov_b64_e32 v[78:79], 0
	v_mov_b64_e32 v[80:81], 0
	v_mov_b64_e32 v[82:83], 0
	v_mov_b64_e32 v[84:85], 0
	v_mov_b64_e32 v[86:87], 0
	v_mov_b64_e32 v[88:89], 0
	v_mov_b64_e32 v[90:91], 0
	v_mov_b64_e32 v[92:93], 0
	v_mov_b64_e32 v[94:95], 0
	v_mov_b64_e32 v[96:97], 0
	v_mov_b64_e32 v[98:99], 0
	v_mov_b64_e32 v[100:101], 0
	v_mov_b64_e32 v[102:103], 0
	v_mov_b64_e32 v[104:105], 0
	v_mov_b64_e32 v[106:107], 0
	v_mov_b64_e32 v[108:109], 0
	v_mov_b64_e32 v[110:111], 0
	v_mov_b64_e32 v[112:113], 0
	v_mov_b64_e32 v[114:115], 0
	v_mov_b64_e32 v[116:117], 0
	v_mov_b64_e32 v[118:119], 0
	v_mov_b64_e32 v[120:121], 0
	v_mov_b64_e32 v[122:123], 0
	v_mov_b64_e32 v[124:125], 0
	v_mov_b64_e32 v[126:127], 0
	v_mov_b64_e32 v[128:129], 0
	s_addc_u32 s51, s53, 0
	s_mov_b32 s73, -2
	s_add_u32 s52, s50, 0xfff80080
	s_addc_u32 s53, s51, -1
	s_cmp_eq_u32 s73, 28
	s_cselect_b32 s61, s6, s53
	s_cselect_b32 s60, s14, s52
	s_cselect_b32 s53, s17, s49
	s_cselect_b32 s52, s41, s43
